# prio 2 from st-loop entry through the epilogue; prio 0 at acum stage and barrier C
# speedup vs baseline: 1.0067x; 1.0067x over previous
.LBB0_821:
	v_mov_b32_e32 v34, v155
	s_or_b64 s[0:1], s[46:47], s[0:1]
	v_ashrrev_i32_e32 v35, 3, v34
	v_and_b32_e32 v32, 0xffffc, v35
	v_and_b32_e32 v33, 31, v34
	v_add_lshl_u32 v32, v32, s6, 11
	v_or3_b32 v32, v32, s28, v33
	v_or_b32_e32 v36, s22, v33
	v_add_u32_e32 v33, s27, v35
	v_lshlrev_b32_e32 v35, 1, v35
	v_mul_u32_u24_e32 v36, 0x110, v36
	v_and_b32_e32 v35, 8, v35
	v_lshrrev_b32_e32 v34, 1, v34
	v_add3_u32 v35, 0, v36, v35
	v_lshrrev_b32_e32 v36, 3, v33
	v_xor_b32_e32 v36, v36, v34
	v_lshlrev_b32_e32 v36, 4, v36
	v_and_b32_e32 v36, 0xf0, v36
	v_add_u32_e32 v36, v35, v36
	ds_read_b64 v[36:37], v36
	v_lshlrev_b32_e32 v32, 1, v32
	s_add_i32 s35, s35, 1
	s_and_b64 vcc, exec, s[0:1]
	s_waitcnt lgkmcnt(0)
	v_lshlrev_b32_e32 v38, 16, v36
	v_fma_f32 v16, v148, v38, v16
	s_waitcnt vmcnt(15)
	v_lshlrev_b32_e32 v38, 16, v175
	v_mul_f32_e32 v40, 0xbfb8aa3b, v38
	v_exp_f32_e32 v40, v40
	v_and_b32_e32 v36, 0xffff0000, v36
	v_lshlrev_b32_e32 v39, 16, v37
	v_and_b32_e32 v37, 0xffff0000, v37
	v_add_f32_e32 v40, 1.0, v40
	v_rcp_f32_e32 v40, v40
	s_nop 0
	v_mul_f32_e32 v38, v40, v38
	v_mul_f32_e32 v16, v38, v16
	v_cvt_pk_bf16_f32 v16, v16, v49
	global_store_short v32, v16, s[70:71]
	v_fma_f32 v16, v148, v36, v17
	s_waitcnt vmcnt(15)
	v_lshlrev_b32_e32 v17, 16, v174
	v_mul_f32_e32 v36, 0xbfb8aa3b, v17
	v_exp_f32_e32 v36, v36
	s_nop 0
	v_add_f32_e32 v36, 1.0, v36
	v_rcp_f32_e32 v36, v36
	s_nop 0
	v_mul_f32_e32 v17, v36, v17
	v_mul_f32_e32 v16, v17, v16
	v_add_u32_e32 v17, 0x1000, v32
	v_cvt_pk_bf16_f32 v16, v16, v49
	global_store_short v17, v16, s[70:71]
	s_waitcnt vmcnt(15)
	v_lshlrev_b32_e32 v17, 16, v173
	v_fma_f32 v16, v148, v39, v18
	v_mul_f32_e32 v18, 0xbfb8aa3b, v17
	v_exp_f32_e32 v18, v18
	s_nop 0
	v_add_f32_e32 v18, 1.0, v18
	v_rcp_f32_e32 v18, v18
	s_nop 0
	v_mul_f32_e32 v17, v18, v17
	v_mul_f32_e32 v16, v17, v16
	v_add_u32_e32 v17, 0x2000, v32
	v_cvt_pk_bf16_f32 v16, v16, v49
	global_store_short v17, v16, s[70:71]
	s_waitcnt vmcnt(15)
	v_lshlrev_b32_e32 v17, 16, v172
	v_mul_f32_e32 v18, 0xbfb8aa3b, v17
	v_exp_f32_e32 v18, v18
	v_fma_f32 v16, v148, v37, v19
	v_add_f32_e32 v18, 1.0, v18
	v_rcp_f32_e32 v18, v18
	s_nop 0
	v_mul_f32_e32 v17, v18, v17
	v_mul_f32_e32 v16, v17, v16
	v_cvt_pk_bf16_f32 v16, v16, v49
	v_add_u32_e32 v17, 0x3000, v32
	global_store_short v17, v16, s[70:71]
	v_add_u32_e32 v16, 8, v33
	v_lshrrev_b32_e32 v16, 3, v16
	v_xor_b32_e32 v16, v16, v34
	v_lshlrev_b32_e32 v16, 4, v16
	v_and_b32_e32 v16, 0xf0, v16
	v_add_u32_e32 v16, v35, v16
	ds_read_b64 v[16:17], v16
	s_waitcnt lgkmcnt(0)
	v_lshlrev_b32_e32 v18, 16, v16
	v_fma_f32 v18, v148, v18, v20
	s_waitcnt vmcnt(15)
	v_lshlrev_b32_e32 v20, 16, v171
	v_mul_f32_e32 v36, 0xbfb8aa3b, v20
	v_exp_f32_e32 v36, v36
	v_and_b32_e32 v16, 0xffff0000, v16
	v_fma_f32 v16, v148, v16, v21
	v_lshlrev_b32_e32 v19, 16, v17
	v_add_f32_e32 v36, 1.0, v36
	v_rcp_f32_e32 v36, v36
	v_and_b32_e32 v17, 0xffff0000, v17
	v_mul_f32_e32 v20, v36, v20
	v_mul_f32_e32 v18, v20, v18
	v_cvt_pk_bf16_f32 v18, v18, v49
	v_add_u32_e32 v20, 0x8000, v32
	global_store_short v20, v18, s[70:71]
	s_waitcnt vmcnt(15)
	v_lshlrev_b32_e32 v18, 16, v170
	v_mul_f32_e32 v20, 0xbfb8aa3b, v18
	v_exp_f32_e32 v20, v20
	s_nop 0
	v_add_f32_e32 v20, 1.0, v20
	v_rcp_f32_e32 v20, v20
	s_nop 0
	v_mul_f32_e32 v18, v20, v18
	v_mul_f32_e32 v16, v18, v16
	v_add_u32_e32 v18, 0x9000, v32
	v_cvt_pk_bf16_f32 v16, v16, v49
	global_store_short v18, v16, s[70:71]
	s_waitcnt vmcnt(15)
	v_lshlrev_b32_e32 v18, 16, v169
	v_fma_f32 v16, v148, v19, v22
	v_mul_f32_e32 v19, 0xbfb8aa3b, v18
	v_exp_f32_e32 v19, v19
	s_waitcnt vmcnt(13)
	v_lshlrev_b32_e32 v20, 16, v167
	v_mul_f32_e32 v21, 0xbfb8aa3b, v20
	v_exp_f32_e32 v21, v21
	v_add_f32_e32 v19, 1.0, v19
	v_rcp_f32_e32 v19, v19
	v_add_f32_e32 v21, 1.0, v21
	v_rcp_f32_e32 v21, v21
	v_mul_f32_e32 v18, v19, v18
	v_mul_f32_e32 v16, v18, v16
	v_cvt_pk_bf16_f32 v16, v16, v49
	v_add_u32_e32 v18, 0xa000, v32
	global_store_short v18, v16, s[70:71]
	v_fma_f32 v16, v148, v17, v23
	v_lshlrev_b32_e32 v17, 16, v168
	v_mul_f32_e32 v18, 0xbfb8aa3b, v17
	v_exp_f32_e32 v18, v18
	v_mul_f32_e32 v20, v21, v20
	v_add_f32_e32 v18, 1.0, v18
	v_rcp_f32_e32 v18, v18
	s_nop 0
	v_mul_f32_e32 v17, v18, v17
	v_mul_f32_e32 v16, v17, v16
	v_cvt_pk_bf16_f32 v16, v16, v49
	v_add_u32_e32 v17, 0xb000, v32
	global_store_short v17, v16, s[70:71]
	v_add_u32_e32 v16, 16, v33
	v_lshrrev_b32_e32 v16, 3, v16
	v_xor_b32_e32 v16, v16, v34
	v_lshlrev_b32_e32 v16, 4, v16
	v_and_b32_e32 v16, 0xf0, v16
	v_add_u32_e32 v16, v35, v16
	ds_read_b64 v[16:17], v16
	s_waitcnt lgkmcnt(0)
	v_lshlrev_b32_e32 v18, 16, v16
	v_fma_f32 v18, v148, v18, v24
	v_mul_f32_e32 v18, v20, v18
	v_cvt_pk_bf16_f32 v18, v18, v49
	v_add_u32_e32 v20, 0x10000, v32
	global_store_short v20, v18, s[70:71]
	s_waitcnt vmcnt(15)
	v_lshlrev_b32_e32 v18, 16, v166
	v_mul_f32_e32 v20, 0xbfb8aa3b, v18
	v_exp_f32_e32 v20, v20
	v_and_b32_e32 v16, 0xffff0000, v16
	v_fma_f32 v16, v148, v16, v25
	v_lshlrev_b32_e32 v19, 16, v17
	v_add_f32_e32 v20, 1.0, v20
	v_rcp_f32_e32 v20, v20
	v_and_b32_e32 v17, 0xffff0000, v17
	v_mul_f32_e32 v18, v20, v18
	v_mul_f32_e32 v16, v18, v16
	v_add_u32_e32 v18, 0x11000, v32
	v_cvt_pk_bf16_f32 v16, v16, v49
	global_store_short v18, v16, s[70:71]
	s_waitcnt vmcnt(15)
	v_lshlrev_b32_e32 v18, 16, v165
	v_fma_f32 v16, v148, v19, v26
	v_mul_f32_e32 v19, 0xbfb8aa3b, v18
	v_exp_f32_e32 v19, v19
	s_waitcnt vmcnt(13)
	v_lshlrev_b32_e32 v20, 16, v163
	v_mul_f32_e32 v21, 0xbfb8aa3b, v20
	v_exp_f32_e32 v21, v21
	v_add_f32_e32 v19, 1.0, v19
	v_rcp_f32_e32 v19, v19
	v_add_f32_e32 v21, 1.0, v21
	v_rcp_f32_e32 v21, v21
	v_mul_f32_e32 v18, v19, v18
	v_mul_f32_e32 v16, v18, v16
	v_cvt_pk_bf16_f32 v16, v16, v49
	v_add_u32_e32 v18, 0x12000, v32
	global_store_short v18, v16, s[70:71]
	v_fma_f32 v16, v148, v17, v27
	v_lshlrev_b32_e32 v17, 16, v164
	v_mul_f32_e32 v18, 0xbfb8aa3b, v17
	v_exp_f32_e32 v18, v18
	v_mul_f32_e32 v20, v21, v20
	v_add_f32_e32 v18, 1.0, v18
	v_rcp_f32_e32 v18, v18
	s_nop 0
	v_mul_f32_e32 v17, v18, v17
	v_mul_f32_e32 v16, v17, v16
	v_cvt_pk_bf16_f32 v16, v16, v49
	v_add_u32_e32 v17, 0x13000, v32
	global_store_short v17, v16, s[70:71]
	v_add_u32_e32 v16, 24, v33
	v_lshrrev_b32_e32 v16, 3, v16
	v_xor_b32_e32 v16, v16, v34
	v_lshlrev_b32_e32 v16, 4, v16
	v_and_b32_e32 v16, 0xf0, v16
	v_add_u32_e32 v16, v35, v16
	ds_read_b64 v[16:17], v16
	s_waitcnt lgkmcnt(0)
	v_lshlrev_b32_e32 v18, 16, v16
	v_fma_f32 v18, v148, v18, v28
	v_mul_f32_e32 v18, v20, v18
	v_cvt_pk_bf16_f32 v18, v18, v49
	v_add_u32_e32 v20, 0x18000, v32
	global_store_short v20, v18, s[70:71]
	s_waitcnt vmcnt(15)
	v_lshlrev_b32_e32 v18, 16, v162
	v_mul_f32_e32 v20, 0xbfb8aa3b, v18
	v_exp_f32_e32 v20, v20
	v_and_b32_e32 v16, 0xffff0000, v16
	v_fma_f32 v16, v148, v16, v29
	v_lshlrev_b32_e32 v19, 16, v17
	v_add_f32_e32 v20, 1.0, v20
	v_rcp_f32_e32 v20, v20
	v_and_b32_e32 v17, 0xffff0000, v17
	v_fmac_f32_e32 v31, v148, v17
	v_mul_f32_e32 v18, v20, v18
	v_mul_f32_e32 v16, v18, v16
	v_add_u32_e32 v18, 0x19000, v32
	v_cvt_pk_bf16_f32 v16, v16, v49
	global_store_short v18, v16, s[70:71]
	s_waitcnt vmcnt(15)
	v_lshlrev_b32_e32 v18, 16, v146
	v_fma_f32 v16, v148, v19, v30
	v_mul_f32_e32 v19, 0xbfb8aa3b, v18
	v_exp_f32_e32 v19, v19
	s_nop 0
	v_add_f32_e32 v19, 1.0, v19
	v_rcp_f32_e32 v19, v19
	s_nop 0
	v_mul_f32_e32 v18, v19, v18
	v_mul_f32_e32 v16, v18, v16
	v_cvt_pk_bf16_f32 v16, v16, v49
	v_add_u32_e32 v18, 0x1a000, v32
	global_store_short v18, v16, s[70:71]
	s_waitcnt vmcnt(15)
	v_lshlrev_b32_e32 v16, 16, v51
	v_mul_f32_e32 v17, 0xbfb8aa3b, v16
	v_exp_f32_e32 v17, v17
	s_nop 0
	v_add_f32_e32 v17, 1.0, v17
	v_rcp_f32_e32 v17, v17
	s_nop 0
	v_mul_f32_e32 v16, v17, v16
	v_mul_f32_e32 v16, v16, v31
	v_add_u32_e32 v17, 0x1b000, v32
	v_cvt_pk_bf16_f32 v16, v16, v49
	global_store_short v17, v16, s[70:71]
	s_cbranch_vccnz .LBB0_780
	s_setprio 0
	v_add_f32_e32 v146, v149, v156
	v_mov_b32_e32 v16, v155
	v_cmp_nlt_f32_e32 vcc, s19, v146
	s_and_saveexec_b64 s[0:1], vcc
	s_cbranch_execz .LBB0_824
	v_mul_f32_e32 v17, 0x3fb8aa3b, v146
	v_exp_f32_e32 v17, v17
	s_mov_b32 s6, 0x3f317218
	v_add_f32_e32 v20, 1.0, v17
	v_frexp_mant_f32_e32 v22, v20
	v_cvt_f64_f32_e32 v[18:19], v20
	v_frexp_exp_i32_f64_e32 v18, v[18:19]
	v_cmp_gt_f32_e32 vcc, s64, v22
	v_add_f32_e32 v21, -1.0, v20
	v_sub_f32_e32 v23, v21, v20
	v_subbrev_co_u32_e32 v26, vcc, 0, v18, vcc
	v_sub_u32_e32 v18, 0, v26
	v_sub_f32_e32 v21, v17, v21
	v_add_f32_e32 v23, 1.0, v23
	v_ldexp_f32 v19, v20, v18
	v_add_f32_e32 v21, v21, v23
	v_add_f32_e32 v20, -1.0, v19
	v_add_f32_e32 v22, 1.0, v19
	v_ldexp_f32 v18, v21, v18
	v_add_f32_e32 v21, 1.0, v20
	v_add_f32_e32 v23, -1.0, v22
	v_sub_f32_e32 v21, v19, v21
	v_sub_f32_e32 v19, v19, v23
	v_add_f32_e32 v21, v18, v21
	v_add_f32_e32 v18, v18, v19
	v_add_f32_e32 v27, v22, v18
	v_rcp_f32_e32 v29, v27
	v_sub_f32_e32 v19, v27, v22
	v_sub_f32_e32 v28, v18, v19
	v_add_f32_e32 v19, v20, v21
	v_mul_f32_e32 v31, v19, v29
	v_sub_f32_e32 v18, v19, v20
	v_mul_f32_e32 v20, v27, v31
	v_fma_f32 v22, v31, v27, -v20
	v_fmac_f32_e32 v22, v31, v28
	v_sub_f32_e32 v30, v21, v18
	v_add_f32_e32 v18, v20, v22
	v_sub_f32_e32 v21, v19, v18
	v_pk_add_f32 v[24:25], v[18:19], v[20:21] neg_lo:[0,1] neg_hi:[0,1]
	v_mov_b32_e32 v23, v18
	v_pk_add_f32 v[18:19], v[24:25], v[22:23] neg_lo:[0,1] neg_hi:[0,1]
	s_nop 0
	v_add_f32_e32 v19, v30, v19
	v_add_f32_e32 v18, v18, v19
	v_add_f32_e32 v19, v21, v18
	v_mul_f32_e32 v30, v29, v19
	v_mul_f32_e32 v20, v27, v30
	v_fma_f32 v22, v30, v27, -v20
	v_fmac_f32_e32 v22, v30, v28
	v_sub_f32_e32 v21, v21, v19
	v_add_f32_e32 v27, v18, v21
	v_add_f32_e32 v18, v20, v22
	v_sub_f32_e32 v21, v19, v18
	v_pk_add_f32 v[24:25], v[18:19], v[20:21] neg_lo:[0,1] neg_hi:[0,1]
	v_mov_b32_e32 v23, v18
	v_pk_add_f32 v[18:19], v[24:25], v[22:23] neg_lo:[0,1] neg_hi:[0,1]
	s_nop 0
	v_add_f32_e32 v19, v27, v19
	v_add_f32_e32 v18, v18, v19
	v_add_f32_e32 v19, v31, v30
	v_add_f32_e32 v18, v21, v18
	v_sub_f32_e32 v20, v19, v31
	v_mul_f32_e32 v18, v29, v18
	v_sub_f32_e32 v20, v30, v20
	v_add_f32_e32 v20, v20, v18
	v_add_f32_e32 v22, v19, v20
	v_mul_f32_e32 v23, v22, v22
	v_fmamk_f32 v18, v23, 0x3e9b6dac, v236
	v_fmaak_f32 v207, v23, v18, 0x3f2aaada
	v_cvt_f32_i32_e32 v18, v26
	v_sub_f32_e32 v19, v22, v19
	v_sub_f32_e32 v19, v20, v19
	v_ldexp_f32 v24, v19, 1
	v_mul_f32_e32 v19, v22, v23
	v_ldexp_f32 v21, v22, 1
	v_pk_mul_f32 v[22:23], v[18:19], v[206:207]
	s_nop 0
	v_fma_f32 v20, v18, s6, -v22
	v_fmac_f32_e32 v20, 0xb102e308, v18
	v_pk_add_f32 v[18:19], v[22:23], v[20:21]
	s_mov_b32 s6, 0x7f800000
	v_sub_f32_e32 v21, v19, v21
	v_sub_f32_e32 v21, v23, v21
	v_add_f32_e32 v25, v24, v21
	v_mov_b32_e32 v24, v22
	v_pk_add_f32 v[22:23], v[18:19], v[22:23] neg_lo:[0,1] neg_hi:[0,1]
	v_pk_add_f32 v[26:27], v[18:19], v[24:25]
	v_mov_b32_e32 v21, v18
	v_mov_b32_e32 v23, v27
	v_pk_add_f32 v[28:29], v[20:21], v[22:23] neg_lo:[0,1] neg_hi:[0,1]
	v_pk_add_f32 v[20:21], v[20:21], v[22:23]
	v_mov_b32_e32 v24, v25
	v_pk_add_f32 v[22:23], v[20:21], v[18:19] op_sel:[1,0] op_sel_hi:[0,1] neg_lo:[0,1] neg_hi:[0,1]
	v_pk_add_f32 v[30:31], v[26:27], v[22:23] op_sel_hi:[1,0] neg_lo:[0,1] neg_hi:[0,1]
	v_mov_b32_e32 v26, v27
	v_mov_b32_e32 v27, v21
	v_pk_mov_b32 v[22:23], v[18:19], v[22:23] op_sel:[1,0]
	v_mov_b32_e32 v25, v18
	v_pk_add_f32 v[22:23], v[26:27], v[22:23] neg_lo:[0,1] neg_hi:[0,1]
	v_mov_b32_e32 v30, v28
	v_pk_add_f32 v[18:19], v[24:25], v[22:23] neg_lo:[0,1] neg_hi:[0,1]
	v_mov_b32_e32 v29, v21
	v_pk_add_f32 v[22:23], v[30:31], v[18:19]
	v_cmp_neq_f32_e32 vcc, s6, v17
	v_pk_add_f32 v[24:25], v[22:23], v[22:23] op_sel:[0,1] op_sel_hi:[1,0]
	s_mov_b32 s6, 0x33800000
	v_pk_add_f32 v[20:21], v[20:21], v[24:25] op_sel:[1,0] op_sel_hi:[0,1]
	v_mov_b32_e32 v23, v20
	v_pk_add_f32 v[26:27], v[22:23], v[28:29] neg_lo:[0,1] neg_hi:[0,1]
	v_mov_b32_e32 v19, v24
	v_sub_f32_e32 v21, v22, v26
	v_pk_add_f32 v[18:19], v[18:19], v[26:27] neg_lo:[0,1] neg_hi:[0,1]
	v_sub_f32_e32 v21, v28, v21
	v_add_f32_e32 v18, v18, v21
	v_add_f32_e32 v18, v18, v19
	v_add_f32_e32 v18, v20, v18
	v_cndmask_b32_e32 v18, v237, v18, vcc
	v_cmp_ngt_f32_e32 vcc, -1.0, v17
	s_nop 1
	v_cndmask_b32_e32 v18, v238, v18, vcc
	v_cmp_neq_f32_e32 vcc, -1.0, v17
	s_nop 1
	v_cndmask_b32_e32 v18, v239, v18, vcc
	v_cmp_lt_f32_e64 vcc, |v17|, s6
	s_nop 1
	v_cndmask_b32_e32 v146, v18, v17, vcc
